# global attention: next unit's Q rows prefetched into L2 from the final iteration
# baseline (speedup 1.0000x reference)
.Lattn_main:
	s_mov_b32 s84, s7
	s_waitcnt lgkmcnt(7)
	v_mfma_f32_32x32x16_bf16 v[64:79], v[222:225], v[96:99], 0
	ds_read_b128 v[222:225], v186 offset:36864
	v_add_f32_e32 v188, v188, v32
	v_add_f32_e32 v189, v189, v33
	v_cvt_pk_bf16_f32 v32, v32, v33
	v_add_f32_e32 v190, v190, v34
	v_add_f32_e32 v191, v191, v35
	v_cvt_pk_bf16_f32 v33, v34, v35
	v_exp_f32_e32 v48, v48
	v_exp_f32_e32 v49, v49
	s_waitcnt lgkmcnt(7)
	v_mfma_f32_32x32x16_bf16 v[206:221], v[226:229], v[96:99], 0
	ds_read_b128 v[226:229], v186 offset:41472
	v_add_f32_e32 v192, v192, v36
	v_add_f32_e32 v193, v193, v37
	v_cvt_pk_bf16_f32 v34, v36, v37
	v_exp_f32_e32 v50, v50
	v_exp_f32_e32 v51, v51
	s_waitcnt lgkmcnt(7)
	v_mfma_f32_32x32x16_bf16 v[64:79], v[230:233], v[100:103], v[64:79]
	ds_read_b128 v[230:233], v186 offset:36896
	v_add_f32_e32 v194, v194, v38
	v_add_f32_e32 v195, v195, v39
	v_cvt_pk_bf16_f32 v35, v38, v39
	v_exp_f32_e32 v52, v52
	v_exp_f32_e32 v53, v53
	s_waitcnt lgkmcnt(7)
	v_mfma_f32_32x32x16_bf16 v[206:221], v[234:237], v[100:103], v[206:221]
	ds_read_b128 v[234:237], v186 offset:41504
	v_add_f32_e32 v196, v196, v40
	v_add_f32_e32 v197, v197, v41
	v_cvt_pk_bf16_f32 v36, v40, v41
	v_exp_f32_e32 v54, v54
	v_exp_f32_e32 v55, v55
	s_waitcnt lgkmcnt(7)
	v_mfma_f32_32x32x16_bf16 v[64:79], v[138:141], v[104:107], v[64:79]
	ds_read_b128 v[138:141], v186 offset:36928
	v_add_f32_e32 v198, v198, v42
	v_add_f32_e32 v199, v199, v43
	v_cvt_pk_bf16_f32 v37, v42, v43
	v_exp_f32_e32 v56, v56
	v_exp_f32_e32 v57, v57
	s_waitcnt lgkmcnt(7)
	v_mfma_f32_32x32x16_bf16 v[206:221], v[142:145], v[104:107], v[206:221]
	ds_read_b128 v[142:145], v186 offset:41536
	v_add_f32_e32 v200, v200, v44
	v_add_f32_e32 v201, v201, v45
	v_cvt_pk_bf16_f32 v38, v44, v45
	v_exp_f32_e32 v58, v58
	v_exp_f32_e32 v59, v59
	s_waitcnt lgkmcnt(7)
	v_mfma_f32_32x32x16_bf16 v[64:79], v[162:165], v[108:111], v[64:79]
	ds_read_b128 v[162:165], v186 offset:36960
	v_add_f32_e32 v202, v202, v46
	v_add_f32_e32 v203, v203, v47
	v_cvt_pk_bf16_f32 v39, v46, v47
	v_exp_f32_e32 v60, v60
	v_exp_f32_e32 v61, v61
	s_waitcnt lgkmcnt(7)
	v_mfma_f32_32x32x16_bf16 v[206:221], v[132:135], v[108:111], v[206:221]
	ds_read_b128 v[132:135], v186 offset:41568
	v_add_f32_e32 v188, v188, v48
	v_add_f32_e32 v189, v189, v49
	v_cvt_pk_bf16_f32 v48, v48, v49
	v_add_f32_e32 v190, v190, v50
	v_add_f32_e32 v191, v191, v51
	v_cvt_pk_bf16_f32 v49, v50, v51
	v_exp_f32_e32 v62, v62
	v_exp_f32_e32 v63, v63
	s_waitcnt lgkmcnt(7)
	v_mfma_f32_32x32x16_bf16 v[0:15], v[222:225], v[32:35], v[0:15]
	ds_read_b128 v[222:225], v186 offset:18432
	v_add_f32_e32 v192, v192, v52
	v_add_f32_e32 v193, v193, v53
	v_cvt_pk_bf16_f32 v50, v52, v53
	v_exp_f32_e32 v64, v64
	v_exp_f32_e32 v65, v65
	s_waitcnt lgkmcnt(7)
	v_mfma_f32_32x32x16_bf16 v[16:31], v[226:229], v[32:35], v[16:31]
	ds_read_b128 v[226:229], v186 offset:23040
	v_add_f32_e32 v194, v194, v54
	v_add_f32_e32 v195, v195, v55
	v_cvt_pk_bf16_f32 v51, v54, v55
	v_exp_f32_e32 v66, v66
	v_exp_f32_e32 v67, v67
	s_waitcnt lgkmcnt(7)
	v_mfma_f32_32x32x16_bf16 v[0:15], v[230:233], v[36:39], v[0:15]
	ds_read_b128 v[230:233], v186 offset:18464
	v_add_f32_e32 v196, v196, v56
	v_add_f32_e32 v197, v197, v57
	v_cvt_pk_bf16_f32 v52, v56, v57
	v_exp_f32_e32 v68, v68
	v_exp_f32_e32 v69, v69
	v_add_u32_e32 v204, 0xd800, v136
	v_add_u32_e32 v205, 0xf800, v136
	s_waitcnt vmcnt(3)
	ds_write_b128 v168, v[112:115] offset:27648
	s_waitcnt vmcnt(2)
	s_waitcnt lgkmcnt(8)
	v_mfma_f32_32x32x16_bf16 v[16:31], v[234:237], v[36:39], v[16:31]
	ds_read_b128 v[234:237], v186 offset:23072
	v_add_f32_e32 v198, v198, v58
	v_add_f32_e32 v199, v199, v59
	v_cvt_pk_bf16_f32 v53, v58, v59
	v_exp_f32_e32 v70, v70
	v_exp_f32_e32 v71, v71
	ds_write_b128 v168, v[116:119]
	s_waitcnt vmcnt(1)
	ds_write2_b64 v204, v[120:121], v[122:123] offset1:2
	s_waitcnt vmcnt(0)
	ds_write2_b64 v205, v[124:125], v[126:127] offset0:128 offset1:130
	s_waitcnt lgkmcnt(11)
	v_mfma_f32_32x32x16_bf16 v[0:15], v[138:141], v[48:51], v[0:15]
	ds_read_b128 v[138:141], v186 offset:18496
	v_add_f32_e32 v200, v200, v60
	v_add_f32_e32 v201, v201, v61
	v_cvt_pk_bf16_f32 v54, v60, v61
	v_exp_f32_e32 v72, v72
	v_exp_f32_e32 v73, v73
	v_lshl_add_u64 v[120:121], v[128:129], 0, v[150:151]
	v_lshl_add_u64 v[124:125], v[130:131], 0, v[150:151]
	s_mov_b32 s98, 0xd8c8000
	v_lshl_add_u64 v[146:147], v[120:121], 0, s[98:99]
	global_load_dwordx4 v[80:83], v[146:147], off offset:2304
	s_waitcnt lgkmcnt(11)
	v_mfma_f32_32x32x16_bf16 v[16:31], v[142:145], v[48:51], v[16:31]
	ds_read_b128 v[142:145], v186 offset:23104
	v_add_f32_e32 v202, v202, v62
	v_add_f32_e32 v203, v203, v63
	v_cvt_pk_bf16_f32 v55, v62, v63
	v_exp_f32_e32 v74, v74
	v_exp_f32_e32 v75, v75
	s_mov_b32 s98, 0xd8f0000
	v_lshl_add_u64 v[146:147], v[120:121], 0, s[98:99]
	global_load_dwordx4 v[84:87], v[146:147], off offset:2304
	s_mov_b32 s98, 0x17820000
	v_lshl_add_u64 v[146:147], v[124:125], 0, s[98:99]
	s_waitcnt lgkmcnt(11)
	v_mfma_f32_32x32x16_bf16 v[0:15], v[162:165], v[52:55], v[0:15]
	ds_read_b128 v[162:165], v186 offset:18528
	v_exp_f32_e32 v76, v76
	v_exp_f32_e32 v77, v77
	global_load_dwordx4 v[88:91], v[146:147], off
	s_mov_b32 s98, 0x17828000
	v_lshl_add_u64 v[146:147], v[124:125], 0, s[98:99]
	global_load_dwordx4 v[92:95], v[146:147], off
	v_lshl_add_u64 v[128:129], v[128:129], 0, s[26:27]
	s_waitcnt lgkmcnt(11)
	v_mfma_f32_32x32x16_bf16 v[16:31], v[132:135], v[52:55], v[16:31]
	ds_read_b128 v[132:135], v186 offset:23136
	v_exp_f32_e32 v78, v78
	v_exp_f32_e32 v79, v79
	v_lshl_add_u64 v[130:131], v[130:131], 0, s[28:29]
	s_mov_b32 s14, s8
	s_add_i32 s6, s6, 4
	s_add_i32 s8, s8, 4
	s_waitcnt lgkmcnt(11)
	v_mfma_f32_32x32x16_bf16 v[32:47], v[222:225], v[96:99], 0
	ds_read_b128 v[222:225], v186 offset:46080
	v_add_f32_e32 v188, v188, v64
	v_add_f32_e32 v189, v189, v65
	v_cvt_pk_bf16_f32 v64, v64, v65
	v_add_f32_e32 v190, v190, v66
	v_add_f32_e32 v191, v191, v67
	v_cvt_pk_bf16_f32 v65, v66, v67
	v_exp_f32_e32 v206, v206
	v_exp_f32_e32 v207, v207
	s_waitcnt lgkmcnt(11)
	v_mfma_f32_32x32x16_bf16 v[48:63], v[226:229], v[96:99], 0
	ds_read_b128 v[226:229], v186 offset:50688
	v_add_f32_e32 v192, v192, v68
	v_add_f32_e32 v193, v193, v69
	v_cvt_pk_bf16_f32 v66, v68, v69
	v_exp_f32_e32 v208, v208
	v_exp_f32_e32 v209, v209
	s_waitcnt lgkmcnt(11)
	v_mfma_f32_32x32x16_bf16 v[32:47], v[230:233], v[100:103], v[32:47]
	ds_read_b128 v[230:233], v186 offset:46112
	v_add_f32_e32 v194, v194, v70
	v_add_f32_e32 v195, v195, v71
	v_cvt_pk_bf16_f32 v67, v70, v71
	v_exp_f32_e32 v210, v210
	v_exp_f32_e32 v211, v211
	s_waitcnt lgkmcnt(10)
	v_mfma_f32_32x32x16_bf16 v[48:63], v[234:237], v[100:103], v[48:63]
	ds_read_b128 v[234:237], v186 offset:50720
	v_add_f32_e32 v196, v196, v72
	v_add_f32_e32 v197, v197, v73
	v_cvt_pk_bf16_f32 v68, v72, v73
	v_exp_f32_e32 v212, v212
	v_exp_f32_e32 v213, v213
	s_waitcnt lgkmcnt(7)
	v_mfma_f32_32x32x16_bf16 v[32:47], v[138:141], v[104:107], v[32:47]
	ds_read_b128 v[138:141], v186 offset:46144
	v_add_f32_e32 v198, v198, v74
	v_add_f32_e32 v199, v199, v75
	v_cvt_pk_bf16_f32 v69, v74, v75
	v_exp_f32_e32 v214, v214
	v_exp_f32_e32 v215, v215
	s_waitcnt lgkmcnt(7)
	v_mfma_f32_32x32x16_bf16 v[48:63], v[142:145], v[104:107], v[48:63]
	ds_read_b128 v[142:145], v186 offset:50752
	v_add_f32_e32 v200, v200, v76
	v_add_f32_e32 v201, v201, v77
	v_cvt_pk_bf16_f32 v70, v76, v77
	v_exp_f32_e32 v216, v216
	v_exp_f32_e32 v217, v217
	s_waitcnt lgkmcnt(7)
	v_mfma_f32_32x32x16_bf16 v[32:47], v[162:165], v[108:111], v[32:47]
	ds_read_b128 v[162:165], v186 offset:46176
	v_add_f32_e32 v202, v202, v78
	v_add_f32_e32 v203, v203, v79
	v_cvt_pk_bf16_f32 v71, v78, v79
	v_exp_f32_e32 v218, v218
	v_exp_f32_e32 v219, v219
	s_waitcnt lgkmcnt(7)
	v_mfma_f32_32x32x16_bf16 v[48:63], v[132:135], v[108:111], v[48:63]
	ds_read_b128 v[132:135], v186 offset:50784
	v_add_f32_e32 v188, v188, v206
	v_add_f32_e32 v189, v189, v207
	v_cvt_pk_bf16_f32 v206, v206, v207
	v_add_f32_e32 v190, v190, v208
	v_add_f32_e32 v191, v191, v209
	v_cvt_pk_bf16_f32 v207, v208, v209
	v_exp_f32_e32 v220, v220
	v_exp_f32_e32 v221, v221
	s_waitcnt lgkmcnt(7)
	v_mfma_f32_32x32x16_bf16 v[0:15], v[222:225], v[64:67], v[0:15]
	v_add_f32_e32 v192, v192, v210
	v_add_f32_e32 v193, v193, v211
	v_cvt_pk_bf16_f32 v208, v210, v211
	v_exp_f32_e32 v32, v32
	v_exp_f32_e32 v33, v33
	s_waitcnt lgkmcnt(6)
	v_mfma_f32_32x32x16_bf16 v[16:31], v[226:229], v[64:67], v[16:31]
	v_add_f32_e32 v194, v194, v212
	v_add_f32_e32 v195, v195, v213
	v_cvt_pk_bf16_f32 v209, v212, v213
	v_exp_f32_e32 v34, v34
	v_exp_f32_e32 v35, v35
	s_waitcnt lgkmcnt(5)
	v_mfma_f32_32x32x16_bf16 v[0:15], v[230:233], v[68:71], v[0:15]
	v_add_f32_e32 v196, v196, v214
	v_add_f32_e32 v197, v197, v215
	v_cvt_pk_bf16_f32 v210, v214, v215
	v_exp_f32_e32 v36, v36
	v_exp_f32_e32 v37, v37
	s_waitcnt lgkmcnt(4)
	v_mfma_f32_32x32x16_bf16 v[16:31], v[234:237], v[68:71], v[16:31]
	s_waitcnt lgkmcnt(0)
	s_barrier
	ds_read_b128 v[222:225], v186 offset:27648
	ds_read_b128 v[226:229], v186 offset:32256
	ds_read_b128 v[230:233], v186 offset:27680
	ds_read_b128 v[234:237], v186 offset:32288
	v_add_f32_e32 v198, v198, v216
	v_add_f32_e32 v199, v199, v217
	v_cvt_pk_bf16_f32 v211, v216, v217
	v_exp_f32_e32 v38, v38
	v_exp_f32_e32 v39, v39
	v_mfma_f32_32x32x16_bf16 v[0:15], v[138:141], v[206:209], v[0:15]
	ds_read_b128 v[138:141], v186 offset:27712
	v_add_f32_e32 v200, v200, v218
	v_add_f32_e32 v201, v201, v219
	v_cvt_pk_bf16_f32 v212, v218, v219
	v_exp_f32_e32 v40, v40
	v_exp_f32_e32 v41, v41
	v_mfma_f32_32x32x16_bf16 v[16:31], v[142:145], v[206:209], v[16:31]
	ds_read_b128 v[142:145], v186 offset:32320
	v_add_f32_e32 v202, v202, v220
	v_add_f32_e32 v203, v203, v221
	v_cvt_pk_bf16_f32 v213, v220, v221
	v_exp_f32_e32 v42, v42
	v_exp_f32_e32 v43, v43
	v_mfma_f32_32x32x16_bf16 v[0:15], v[162:165], v[210:213], v[0:15]
	ds_read_b128 v[162:165], v186 offset:27744
	v_exp_f32_e32 v44, v44
	v_exp_f32_e32 v45, v45
	v_mfma_f32_32x32x16_bf16 v[16:31], v[132:135], v[210:213], v[16:31]
	ds_read_b128 v[132:135], v186 offset:32352
	v_exp_f32_e32 v46, v46
	v_exp_f32_e32 v47, v47
	s_waitcnt lgkmcnt(7)
	v_mfma_f32_32x32x16_bf16 v[64:79], v[222:225], v[96:99], 0
	ds_read_b128 v[222:225], v186 offset:55296
	v_add_f32_e32 v188, v188, v32
	v_add_f32_e32 v189, v189, v33
	v_cvt_pk_bf16_f32 v32, v32, v33
	v_add_f32_e32 v190, v190, v34
	v_add_f32_e32 v191, v191, v35
	v_cvt_pk_bf16_f32 v33, v34, v35
	v_exp_f32_e32 v48, v48
	v_exp_f32_e32 v49, v49
	s_waitcnt lgkmcnt(7)
	v_mfma_f32_32x32x16_bf16 v[206:221], v[226:229], v[96:99], 0
	ds_read_b128 v[226:229], v186 offset:59904
	v_add_f32_e32 v192, v192, v36
	v_add_f32_e32 v193, v193, v37
	v_cvt_pk_bf16_f32 v34, v36, v37
	v_exp_f32_e32 v50, v50
	v_exp_f32_e32 v51, v51
	s_waitcnt lgkmcnt(7)
	v_mfma_f32_32x32x16_bf16 v[64:79], v[230:233], v[100:103], v[64:79]
	ds_read_b128 v[230:233], v186 offset:55328
	v_add_f32_e32 v194, v194, v38
	v_add_f32_e32 v195, v195, v39
	v_cvt_pk_bf16_f32 v35, v38, v39
	v_exp_f32_e32 v52, v52
	v_exp_f32_e32 v53, v53
	s_waitcnt lgkmcnt(7)
	v_mfma_f32_32x32x16_bf16 v[206:221], v[234:237], v[100:103], v[206:221]
	ds_read_b128 v[234:237], v186 offset:59936
	v_add_f32_e32 v196, v196, v40
	v_add_f32_e32 v197, v197, v41
	v_cvt_pk_bf16_f32 v36, v40, v41
	v_exp_f32_e32 v54, v54
	v_exp_f32_e32 v55, v55
	s_waitcnt lgkmcnt(7)
	v_mfma_f32_32x32x16_bf16 v[64:79], v[138:141], v[104:107], v[64:79]
	ds_read_b128 v[138:141], v186 offset:55360
	v_add_f32_e32 v198, v198, v42
	v_add_f32_e32 v199, v199, v43
	v_cvt_pk_bf16_f32 v37, v42, v43
	v_exp_f32_e32 v56, v56
	v_exp_f32_e32 v57, v57
	s_waitcnt lgkmcnt(7)
	v_mfma_f32_32x32x16_bf16 v[206:221], v[142:145], v[104:107], v[206:221]
	ds_read_b128 v[142:145], v186 offset:59968
	v_add_f32_e32 v200, v200, v44
	v_add_f32_e32 v201, v201, v45
	v_cvt_pk_bf16_f32 v38, v44, v45
	v_exp_f32_e32 v58, v58
	v_exp_f32_e32 v59, v59
	s_waitcnt lgkmcnt(7)
	v_mfma_f32_32x32x16_bf16 v[64:79], v[162:165], v[108:111], v[64:79]
	ds_read_b128 v[162:165], v186 offset:55392
	v_add_f32_e32 v202, v202, v46
	v_add_f32_e32 v203, v203, v47
	v_cvt_pk_bf16_f32 v39, v46, v47
	v_exp_f32_e32 v60, v60
	v_exp_f32_e32 v61, v61
	s_waitcnt lgkmcnt(7)
	v_mfma_f32_32x32x16_bf16 v[206:221], v[132:135], v[108:111], v[206:221]
	ds_read_b128 v[132:135], v186 offset:60000
	v_add_f32_e32 v188, v188, v48
	v_add_f32_e32 v189, v189, v49
	v_cvt_pk_bf16_f32 v48, v48, v49
	v_add_f32_e32 v190, v190, v50
	v_add_f32_e32 v191, v191, v51
	v_cvt_pk_bf16_f32 v49, v50, v51
	v_exp_f32_e32 v62, v62
	v_exp_f32_e32 v63, v63
	s_waitcnt lgkmcnt(7)
	v_mfma_f32_32x32x16_bf16 v[0:15], v[222:225], v[32:35], v[0:15]
	ds_read_b128 v[222:225], v186
	v_add_f32_e32 v192, v192, v52
	v_add_f32_e32 v193, v193, v53
	v_cvt_pk_bf16_f32 v50, v52, v53
	v_exp_f32_e32 v64, v64
	v_exp_f32_e32 v65, v65
	s_waitcnt lgkmcnt(7)
	v_mfma_f32_32x32x16_bf16 v[16:31], v[226:229], v[32:35], v[16:31]
	ds_read_b128 v[226:229], v186 offset:4608
	v_add_f32_e32 v194, v194, v54
	v_add_f32_e32 v195, v195, v55
	v_cvt_pk_bf16_f32 v51, v54, v55
	v_exp_f32_e32 v66, v66
	v_exp_f32_e32 v67, v67
	s_waitcnt lgkmcnt(7)
	v_mfma_f32_32x32x16_bf16 v[0:15], v[230:233], v[36:39], v[0:15]
	ds_read_b128 v[230:233], v186 offset:32
	v_add_f32_e32 v196, v196, v56
	v_add_f32_e32 v197, v197, v57
	v_cvt_pk_bf16_f32 v52, v56, v57
	v_exp_f32_e32 v68, v68
	v_exp_f32_e32 v69, v69
	s_waitcnt vmcnt(3)
	ds_write_b128 v168, v[80:83] offset:9216
	s_waitcnt vmcnt(2)
	ds_write_b128 v168, v[84:87] offset:18432
	s_waitcnt lgkmcnt(9)
	v_mfma_f32_32x32x16_bf16 v[16:31], v[234:237], v[36:39], v[16:31]
	ds_read_b128 v[234:237], v186 offset:4640
	v_add_f32_e32 v198, v198, v58
	v_add_f32_e32 v199, v199, v59
	v_cvt_pk_bf16_f32 v53, v58, v59
	v_exp_f32_e32 v70, v70
	v_exp_f32_e32 v71, v71
	s_waitcnt vmcnt(1)
	ds_write2_b64 v169, v[88:89], v[90:91] offset1:2
	s_waitcnt vmcnt(0)
	ds_write2_b64 v170, v[92:93], v[94:95] offset0:128 offset1:130
	s_waitcnt lgkmcnt(11)
	v_mfma_f32_32x32x16_bf16 v[0:15], v[138:141], v[48:51], v[0:15]
	ds_read_b128 v[138:141], v186 offset:64
	v_add_f32_e32 v200, v200, v60
	v_add_f32_e32 v201, v201, v61
	v_cvt_pk_bf16_f32 v54, v60, v61
	v_exp_f32_e32 v72, v72
	v_exp_f32_e32 v73, v73
	s_mov_b32 s98, 0xd918000
	v_lshl_add_u64 v[146:147], v[120:121], 0, s[98:99]
	global_load_dwordx4 v[112:115], v[146:147], off offset:2304
	s_mov_b32 s98, 0xd940000
	s_waitcnt lgkmcnt(11)
	v_mfma_f32_32x32x16_bf16 v[16:31], v[142:145], v[48:51], v[16:31]
	ds_read_b128 v[142:145], v186 offset:4672
	v_add_f32_e32 v202, v202, v62
	v_add_f32_e32 v203, v203, v63
	v_cvt_pk_bf16_f32 v55, v62, v63
	v_exp_f32_e32 v74, v74
	v_exp_f32_e32 v75, v75
	v_lshl_add_u64 v[146:147], v[120:121], 0, s[98:99]
	global_load_dwordx4 v[116:119], v[146:147], off offset:2304
	s_mov_b32 s98, 0x17830000
	v_lshl_add_u64 v[146:147], v[124:125], 0, s[98:99]
	s_waitcnt lgkmcnt(11)
	v_mfma_f32_32x32x16_bf16 v[0:15], v[162:165], v[52:55], v[0:15]
	ds_read_b128 v[162:165], v186 offset:96
	v_exp_f32_e32 v76, v76
	v_exp_f32_e32 v77, v77
	global_load_dwordx4 v[120:123], v[146:147], off
	s_mov_b32 s98, 0x17838000
	v_lshl_add_u64 v[146:147], v[124:125], 0, s[98:99]
	global_load_dwordx4 v[124:127], v[146:147], off
	s_waitcnt lgkmcnt(11)
	v_mfma_f32_32x32x16_bf16 v[16:31], v[132:135], v[52:55], v[16:31]
	ds_read_b128 v[132:135], v186 offset:4704
	v_exp_f32_e32 v78, v78
	v_exp_f32_e32 v79, v79
	s_add_i32 s7, s84, 4
	s_waitcnt lgkmcnt(11)
	v_mfma_f32_32x32x16_bf16 v[32:47], v[222:225], v[96:99], 0
	ds_read_b128 v[222:225], v186 offset:64512
	v_add_f32_e32 v188, v188, v64
	v_add_f32_e32 v189, v189, v65
	v_cvt_pk_bf16_f32 v64, v64, v65
	v_add_f32_e32 v190, v190, v66
	v_add_f32_e32 v191, v191, v67
	v_cvt_pk_bf16_f32 v65, v66, v67
	v_exp_f32_e32 v206, v206
	v_exp_f32_e32 v207, v207
	s_waitcnt lgkmcnt(11)
	v_mfma_f32_32x32x16_bf16 v[48:63], v[226:229], v[96:99], 0
	ds_read_b128 v[226:229], v187 offset:32256
	v_add_f32_e32 v192, v192, v68
	v_add_f32_e32 v193, v193, v69
	v_cvt_pk_bf16_f32 v66, v68, v69
	v_exp_f32_e32 v208, v208
	v_exp_f32_e32 v209, v209
	s_waitcnt lgkmcnt(11)
	v_mfma_f32_32x32x16_bf16 v[32:47], v[230:233], v[100:103], v[32:47]
	ds_read_b128 v[230:233], v186 offset:64544
	v_add_f32_e32 v194, v194, v70
	v_add_f32_e32 v195, v195, v71
	v_cvt_pk_bf16_f32 v67, v70, v71
	v_exp_f32_e32 v210, v210
	v_exp_f32_e32 v211, v211
	s_waitcnt lgkmcnt(9)
	v_mfma_f32_32x32x16_bf16 v[48:63], v[234:237], v[100:103], v[48:63]
	ds_read_b128 v[234:237], v187 offset:32288
	v_add_f32_e32 v196, v196, v72
	v_add_f32_e32 v197, v197, v73
	v_cvt_pk_bf16_f32 v68, v72, v73
	v_exp_f32_e32 v212, v212
	v_exp_f32_e32 v213, v213
	s_waitcnt lgkmcnt(7)
	v_mfma_f32_32x32x16_bf16 v[32:47], v[138:141], v[104:107], v[32:47]
	ds_read_b128 v[138:141], v186 offset:64576
	v_add_f32_e32 v198, v198, v74
	v_add_f32_e32 v199, v199, v75
	v_cvt_pk_bf16_f32 v69, v74, v75
	v_exp_f32_e32 v214, v214
	v_exp_f32_e32 v215, v215
	s_waitcnt lgkmcnt(7)
; __device__ __forceinline__ void attn_global(LAS unsigned char* lds, const bf16_t* __restrict__ PROJ, const bf16_t* __restrict__ VT, bf16_t* __restrict__ AO,
;                                             int rowbase, int S, int hq, int q0, float bound2) {
;     ...
;     int t = 0;
; #pragma unroll 1
;     for (; t + 10 < T; t += 4) { ATT_DSTEP(t, 0, true); ATT_DSTEP(t + 2, 2, true); }
	v_mfma_f32_32x32x16_bf16 v[48:63], v[142:145], v[104:107], v[48:63]
	ds_read_b128 v[142:145], v187 offset:32320
	v_add_f32_e32 v200, v200, v76
	v_add_f32_e32 v201, v201, v77
	v_cvt_pk_bf16_f32 v70, v76, v77
	v_exp_f32_e32 v216, v216
	v_exp_f32_e32 v217, v217
	s_waitcnt lgkmcnt(7)
	v_mfma_f32_32x32x16_bf16 v[32:47], v[162:165], v[108:111], v[32:47]
	ds_read_b128 v[162:165], v186 offset:64608
	v_add_f32_e32 v202, v202, v78
	v_add_f32_e32 v203, v203, v79
	v_cvt_pk_bf16_f32 v71, v78, v79
	v_exp_f32_e32 v218, v218
	v_exp_f32_e32 v219, v219
	s_waitcnt lgkmcnt(7)
	v_mfma_f32_32x32x16_bf16 v[48:63], v[132:135], v[108:111], v[48:63]
	ds_read_b128 v[132:135], v187 offset:32352
	v_add_f32_e32 v188, v188, v206
	v_add_f32_e32 v189, v189, v207
	v_cvt_pk_bf16_f32 v206, v206, v207
	v_add_f32_e32 v190, v190, v208
	v_add_f32_e32 v191, v191, v209
	v_cvt_pk_bf16_f32 v207, v208, v209
	v_exp_f32_e32 v220, v220
	v_exp_f32_e32 v221, v221
	s_waitcnt lgkmcnt(7)
	v_mfma_f32_32x32x16_bf16 v[0:15], v[222:225], v[64:67], v[0:15]
	v_add_f32_e32 v192, v192, v210
	v_add_f32_e32 v193, v193, v211
	v_cvt_pk_bf16_f32 v208, v210, v211
	v_exp_f32_e32 v32, v32
	v_exp_f32_e32 v33, v33
	s_waitcnt lgkmcnt(6)
	v_mfma_f32_32x32x16_bf16 v[16:31], v[226:229], v[64:67], v[16:31]
	v_add_f32_e32 v194, v194, v212
	v_add_f32_e32 v195, v195, v213
	v_cvt_pk_bf16_f32 v209, v212, v213
	v_exp_f32_e32 v34, v34
	v_exp_f32_e32 v35, v35
	s_waitcnt lgkmcnt(5)
	v_mfma_f32_32x32x16_bf16 v[0:15], v[230:233], v[68:71], v[0:15]
	v_add_f32_e32 v196, v196, v214
	v_add_f32_e32 v197, v197, v215
	v_cvt_pk_bf16_f32 v210, v214, v215
	v_exp_f32_e32 v36, v36
	v_exp_f32_e32 v37, v37
	s_waitcnt lgkmcnt(4)
	v_mfma_f32_32x32x16_bf16 v[16:31], v[234:237], v[68:71], v[16:31]
	s_waitcnt lgkmcnt(0)
	s_barrier
	ds_read_b128 v[222:225], v186 offset:9216
	ds_read_b128 v[226:229], v186 offset:13824
	ds_read_b128 v[230:233], v186 offset:9248
	ds_read_b128 v[234:237], v186 offset:13856
	v_add_f32_e32 v198, v198, v216
	v_add_f32_e32 v199, v199, v217
	v_cvt_pk_bf16_f32 v211, v216, v217
	v_exp_f32_e32 v38, v38
	v_exp_f32_e32 v39, v39
	v_mfma_f32_32x32x16_bf16 v[0:15], v[138:141], v[206:209], v[0:15]
	ds_read_b128 v[138:141], v186 offset:9280
	v_add_f32_e32 v200, v200, v218
	v_add_f32_e32 v201, v201, v219
	v_cvt_pk_bf16_f32 v212, v218, v219
	v_exp_f32_e32 v40, v40
	v_exp_f32_e32 v41, v41
	v_mfma_f32_32x32x16_bf16 v[16:31], v[142:145], v[206:209], v[16:31]
	ds_read_b128 v[142:145], v186 offset:13888
	v_add_f32_e32 v202, v202, v220
	v_add_f32_e32 v203, v203, v221
	v_cvt_pk_bf16_f32 v213, v220, v221
	v_exp_f32_e32 v42, v42
	v_exp_f32_e32 v43, v43
	v_mfma_f32_32x32x16_bf16 v[0:15], v[162:165], v[210:213], v[0:15]
	ds_read_b128 v[162:165], v186 offset:9312
	v_exp_f32_e32 v44, v44
	v_exp_f32_e32 v45, v45
	v_mfma_f32_32x32x16_bf16 v[16:31], v[132:135], v[210:213], v[16:31]
	ds_read_b128 v[132:135], v186 offset:13920
	v_exp_f32_e32 v46, v46
	v_exp_f32_e32 v47, v47
	v_lshl_add_u64 v[158:159], v[158:159], 0, s[26:27]
	v_lshl_add_u64 v[160:161], v[160:161], 0, s[28:29]
	s_sub_u32 s98, s6, 6
	s_cmp_ge_u32 s98, s82
	s_cbranch_scc0 .Lattn_main
	s_mov_b32 s84, s7
	s_waitcnt lgkmcnt(7)
	v_mfma_f32_32x32x16_bf16 v[64:79], v[222:225], v[96:99], 0
	ds_read_b128 v[222:225], v186 offset:36864
	v_add_f32_e32 v188, v188, v32
	v_add_f32_e32 v189, v189, v33
	v_cvt_pk_bf16_f32 v32, v32, v33
	v_add_f32_e32 v190, v190, v34
	v_add_f32_e32 v191, v191, v35
	v_cvt_pk_bf16_f32 v33, v34, v35
	v_exp_f32_e32 v48, v48
	v_exp_f32_e32 v49, v49
	s_waitcnt lgkmcnt(7)
	v_mfma_f32_32x32x16_bf16 v[206:221], v[226:229], v[96:99], 0
	ds_read_b128 v[226:229], v186 offset:41472
	v_add_f32_e32 v192, v192, v36
	v_add_f32_e32 v193, v193, v37
	v_cvt_pk_bf16_f32 v34, v36, v37
	v_exp_f32_e32 v50, v50
	v_exp_f32_e32 v51, v51
	s_waitcnt lgkmcnt(7)
	v_mfma_f32_32x32x16_bf16 v[64:79], v[230:233], v[100:103], v[64:79]
	ds_read_b128 v[230:233], v186 offset:36896
	v_add_f32_e32 v194, v194, v38
	v_add_f32_e32 v195, v195, v39
	v_cvt_pk_bf16_f32 v35, v38, v39
	v_exp_f32_e32 v52, v52
	v_exp_f32_e32 v53, v53
	s_waitcnt lgkmcnt(7)
	v_mfma_f32_32x32x16_bf16 v[206:221], v[234:237], v[100:103], v[206:221]
	ds_read_b128 v[234:237], v186 offset:41504
	v_add_f32_e32 v196, v196, v40
	v_add_f32_e32 v197, v197, v41
	v_cvt_pk_bf16_f32 v36, v40, v41
	v_exp_f32_e32 v54, v54
	v_exp_f32_e32 v55, v55
	s_waitcnt lgkmcnt(7)
	v_mfma_f32_32x32x16_bf16 v[64:79], v[138:141], v[104:107], v[64:79]
	ds_read_b128 v[138:141], v186 offset:36928
	v_add_f32_e32 v198, v198, v42
	v_add_f32_e32 v199, v199, v43
	v_cvt_pk_bf16_f32 v37, v42, v43
	v_exp_f32_e32 v56, v56
	v_exp_f32_e32 v57, v57
	s_waitcnt lgkmcnt(7)
	v_mfma_f32_32x32x16_bf16 v[206:221], v[142:145], v[104:107], v[206:221]
	ds_read_b128 v[142:145], v186 offset:41536
	v_add_f32_e32 v200, v200, v44
	v_add_f32_e32 v201, v201, v45
	v_cvt_pk_bf16_f32 v38, v44, v45
	v_exp_f32_e32 v58, v58
	v_exp_f32_e32 v59, v59
	s_waitcnt lgkmcnt(7)
	v_mfma_f32_32x32x16_bf16 v[64:79], v[162:165], v[108:111], v[64:79]
	ds_read_b128 v[162:165], v186 offset:36960
	v_add_f32_e32 v202, v202, v46
	v_add_f32_e32 v203, v203, v47
	v_cvt_pk_bf16_f32 v39, v46, v47
	v_exp_f32_e32 v60, v60
	v_exp_f32_e32 v61, v61
	s_waitcnt lgkmcnt(7)
	v_mfma_f32_32x32x16_bf16 v[206:221], v[132:135], v[108:111], v[206:221]
	ds_read_b128 v[132:135], v186 offset:41568
	v_add_f32_e32 v188, v188, v48
	v_add_f32_e32 v189, v189, v49
	v_cvt_pk_bf16_f32 v48, v48, v49
	v_add_f32_e32 v190, v190, v50
	v_add_f32_e32 v191, v191, v51
	v_cvt_pk_bf16_f32 v49, v50, v51
	v_exp_f32_e32 v62, v62
	v_exp_f32_e32 v63, v63
	s_waitcnt lgkmcnt(7)
; __global__ void __launch_bounds__(NWAVES * 64, 2) mega_fwd(Args a_unused) {
;     ...
;             for (int u = I.vcu; u < 4096; u += I.G) {
;                 const int kind = u >> 10, idx = u & 1023; const bool sample = kind & 1, win = kind >= 2;
;                 const int S = sample ? 8192 : 4096, nqb = S >> 8, per = 4 * nqb;
;                 const int bk = idx / per, rem = idx % per, b = bk >> 1, kvh = bk & 1, hq = kvh * 4 + rem / nqb, qb = rem % nqb;
;                 const int rowbase = (sample ? MHALF : 0) + b * S;
;                 if (win) att::attn_win(lds, PROJ, VT, AO, rowbase, S, kvh, rem * 64, lutg, sinkp);
;                 else att::attn_global(lds, PROJ, VT, AO, rowbase, S, hq, qb * 256, bound2);
	v_mfma_f32_32x32x16_bf16 v[0:15], v[222:225], v[32:35], v[0:15]
	ds_read_b128 v[222:225], v186 offset:18432
	v_add_f32_e32 v192, v192, v52
	v_add_f32_e32 v193, v193, v53
	v_cvt_pk_bf16_f32 v50, v52, v53
	v_exp_f32_e32 v64, v64
	v_exp_f32_e32 v65, v65
	s_waitcnt lgkmcnt(7)
	v_mfma_f32_32x32x16_bf16 v[16:31], v[226:229], v[32:35], v[16:31]
	ds_read_b128 v[226:229], v186 offset:23040
	v_add_f32_e32 v194, v194, v54
	v_add_f32_e32 v195, v195, v55
	v_cvt_pk_bf16_f32 v51, v54, v55
	v_exp_f32_e32 v66, v66
	v_exp_f32_e32 v67, v67
	s_waitcnt lgkmcnt(7)
	v_mfma_f32_32x32x16_bf16 v[0:15], v[230:233], v[36:39], v[0:15]
	ds_read_b128 v[230:233], v186 offset:18464
	v_add_f32_e32 v196, v196, v56
	v_add_f32_e32 v197, v197, v57
	v_cvt_pk_bf16_f32 v52, v56, v57
	v_exp_f32_e32 v68, v68
	v_exp_f32_e32 v69, v69
	v_add_u32_e32 v204, 0xd800, v136
	v_add_u32_e32 v205, 0xf800, v136
	s_waitcnt vmcnt(3)
	s_waitcnt lgkmcnt(7)
	v_mfma_f32_32x32x16_bf16 v[16:31], v[234:237], v[36:39], v[16:31]
	ds_read_b128 v[234:237], v186 offset:23072
	v_add_f32_e32 v198, v198, v58
	v_add_f32_e32 v199, v199, v59
	v_cvt_pk_bf16_f32 v53, v58, v59
	v_exp_f32_e32 v70, v70
	v_exp_f32_e32 v71, v71
	ds_write_b128 v168, v[112:115] offset:27648
	s_waitcnt vmcnt(2)
	ds_write_b128 v168, v[116:119]
	s_waitcnt lgkmcnt(9)
	v_mfma_f32_32x32x16_bf16 v[0:15], v[138:141], v[48:51], v[0:15]
	ds_read_b128 v[138:141], v186 offset:18496
	v_add_f32_e32 v200, v200, v60
	v_add_f32_e32 v201, v201, v61
	v_cvt_pk_bf16_f32 v54, v60, v61
	v_exp_f32_e32 v72, v72
	v_exp_f32_e32 v73, v73
	s_waitcnt vmcnt(1)
	ds_write2_b64 v204, v[120:121], v[122:123] offset1:2
	s_waitcnt vmcnt(0)
	s_waitcnt lgkmcnt(10)
	v_mfma_f32_32x32x16_bf16 v[16:31], v[142:145], v[48:51], v[16:31]
	ds_read_b128 v[142:145], v186 offset:23104
	v_add_f32_e32 v202, v202, v62
	v_add_f32_e32 v203, v203, v63
	v_cvt_pk_bf16_f32 v55, v62, v63
	v_exp_f32_e32 v74, v74
	v_exp_f32_e32 v75, v75
	ds_write2_b64 v205, v[124:125], v[126:127] offset0:128 offset1:130
	v_lshl_add_u64 v[120:121], v[128:129], 0, v[150:151]
	v_lshl_add_u64 v[124:125], v[130:131], 0, v[150:151]
	s_waitcnt lgkmcnt(11)
	v_mfma_f32_32x32x16_bf16 v[0:15], v[162:165], v[52:55], v[0:15]
	ds_read_b128 v[162:165], v186 offset:18528
	v_exp_f32_e32 v76, v76
	v_exp_f32_e32 v77, v77
	v_lshl_add_u64 v[128:129], v[128:129], 0, s[26:27]
	v_lshl_add_u64 v[130:131], v[130:131], 0, s[28:29]
	s_mov_b32 s14, s8
	s_waitcnt lgkmcnt(11)
	v_mfma_f32_32x32x16_bf16 v[16:31], v[132:135], v[52:55], v[16:31]
	ds_read_b128 v[132:135], v186 offset:23136
	v_exp_f32_e32 v78, v78
	v_exp_f32_e32 v79, v79
	s_add_i32 s6, s6, 4
	s_add_i32 s8, s8, 4
	v_add_u32_e32 v137, 0x2000, v156
	v_mov_b64_e32 v[146:147], s[48:49]
	s_lshl_b32 s98, s83, 1
	v_mad_i64_i32 v[146:147], s[100:101], v137, s92, v[146:147]
	s_addk_i32 s98, 0x400
	v_lshl_add_u64 v[146:147], v[146:147], 0, s[98:99]
	global_load_dword v137, v[146:147], off
	s_waitcnt lgkmcnt(11)
	v_mfma_f32_32x32x16_bf16 v[32:47], v[222:225], v[96:99], 0
	ds_read_b128 v[222:225], v186 offset:46080
	v_add_f32_e32 v188, v188, v64
	v_add_f32_e32 v189, v189, v65
	v_cvt_pk_bf16_f32 v64, v64, v65
	v_add_f32_e32 v190, v190, v66
	v_add_f32_e32 v191, v191, v67
	v_cvt_pk_bf16_f32 v65, v66, v67
	v_exp_f32_e32 v206, v206
	v_exp_f32_e32 v207, v207
	s_waitcnt lgkmcnt(11)
	v_mfma_f32_32x32x16_bf16 v[48:63], v[226:229], v[96:99], 0
	ds_read_b128 v[226:229], v186 offset:50688
	v_add_f32_e32 v192, v192, v68
	v_add_f32_e32 v193, v193, v69
	v_cvt_pk_bf16_f32 v66, v68, v69
	v_exp_f32_e32 v208, v208
	v_exp_f32_e32 v209, v209
	s_waitcnt lgkmcnt(11)
	v_mfma_f32_32x32x16_bf16 v[32:47], v[230:233], v[100:103], v[32:47]
	ds_read_b128 v[230:233], v186 offset:46112
	v_add_f32_e32 v194, v194, v70
	v_add_f32_e32 v195, v195, v71
	v_cvt_pk_bf16_f32 v67, v70, v71
	v_exp_f32_e32 v210, v210
	v_exp_f32_e32 v211, v211
	s_waitcnt lgkmcnt(11)
	v_mfma_f32_32x32x16_bf16 v[48:63], v[234:237], v[100:103], v[48:63]
	ds_read_b128 v[234:237], v186 offset:50720
	v_add_f32_e32 v196, v196, v72
	v_add_f32_e32 v197, v197, v73
	v_cvt_pk_bf16_f32 v68, v72, v73
	v_exp_f32_e32 v212, v212
	v_exp_f32_e32 v213, v213
	s_waitcnt lgkmcnt(9)
	v_mfma_f32_32x32x16_bf16 v[32:47], v[138:141], v[104:107], v[32:47]
	ds_read_b128 v[138:141], v186 offset:46144
	v_add_f32_e32 v198, v198, v74
	v_add_f32_e32 v199, v199, v75
	v_cvt_pk_bf16_f32 v69, v74, v75
	v_exp_f32_e32 v214, v214
	v_exp_f32_e32 v215, v215
	s_waitcnt lgkmcnt(8)
	v_mfma_f32_32x32x16_bf16 v[48:63], v[142:145], v[104:107], v[48:63]
	ds_read_b128 v[142:145], v186 offset:50752
	v_add_f32_e32 v200, v200, v76
	v_add_f32_e32 v201, v201, v77
	v_cvt_pk_bf16_f32 v70, v76, v77
	v_exp_f32_e32 v216, v216
	v_exp_f32_e32 v217, v217
	s_waitcnt lgkmcnt(7)
	v_mfma_f32_32x32x16_bf16 v[32:47], v[162:165], v[108:111], v[32:47]
	ds_read_b128 v[162:165], v186 offset:46176
	v_add_f32_e32 v202, v202, v78
	v_add_f32_e32 v203, v203, v79
	v_cvt_pk_bf16_f32 v71, v78, v79
	v_exp_f32_e32 v218, v218
	v_exp_f32_e32 v219, v219
	s_waitcnt lgkmcnt(7)
	v_mfma_f32_32x32x16_bf16 v[48:63], v[132:135], v[108:111], v[48:63]
	ds_read_b128 v[132:135], v186 offset:50784
	v_add_f32_e32 v188, v188, v206
	v_add_f32_e32 v189, v189, v207
	v_cvt_pk_bf16_f32 v206, v206, v207
	v_add_f32_e32 v190, v190, v208
	v_add_f32_e32 v191, v191, v209
	v_cvt_pk_bf16_f32 v207, v208, v209
	v_exp_f32_e32 v220, v220
	v_exp_f32_e32 v221, v221
	s_waitcnt lgkmcnt(7)
	v_mfma_f32_32x32x16_bf16 v[0:15], v[222:225], v[64:67], v[0:15]
	v_add_f32_e32 v192, v192, v210
	v_add_f32_e32 v193, v193, v211
	v_cvt_pk_bf16_f32 v208, v210, v211
	v_exp_f32_e32 v32, v32
	v_exp_f32_e32 v33, v33
	s_waitcnt lgkmcnt(6)
	v_mfma_f32_32x32x16_bf16 v[16:31], v[226:229], v[64:67], v[16:31]
	v_add_f32_e32 v194, v194, v212
	v_add_f32_e32 v195, v195, v213
	v_cvt_pk_bf16_f32 v209, v212, v213
	v_exp_f32_e32 v34, v34
	v_exp_f32_e32 v35, v35
	s_waitcnt lgkmcnt(5)
	v_mfma_f32_32x32x16_bf16 v[0:15], v[230:233], v[68:71], v[0:15]
	v_add_f32_e32 v196, v196, v214
	v_add_f32_e32 v197, v197, v215
	v_cvt_pk_bf16_f32 v210, v214, v215
	v_exp_f32_e32 v36, v36
	v_exp_f32_e32 v37, v37
	s_waitcnt lgkmcnt(4)
	v_mfma_f32_32x32x16_bf16 v[16:31], v[234:237], v[68:71], v[16:31]
	s_waitcnt lgkmcnt(0)
	s_barrier
	ds_read_b128 v[222:225], v186 offset:27648
	ds_read_b128 v[226:229], v186 offset:32256
	ds_read_b128 v[230:233], v186 offset:27680
	ds_read_b128 v[234:237], v186 offset:32288
	v_add_f32_e32 v198, v198, v216
	v_add_f32_e32 v199, v199, v217
	v_cvt_pk_bf16_f32 v211, v216, v217
	v_exp_f32_e32 v38, v38
	v_exp_f32_e32 v39, v39
	v_mfma_f32_32x32x16_bf16 v[0:15], v[138:141], v[206:209], v[0:15]
	ds_read_b128 v[138:141], v186 offset:27712
	v_add_f32_e32 v200, v200, v218
	v_add_f32_e32 v201, v201, v219
	v_cvt_pk_bf16_f32 v212, v218, v219
	v_exp_f32_e32 v40, v40
	v_exp_f32_e32 v41, v41
	v_mfma_f32_32x32x16_bf16 v[16:31], v[142:145], v[206:209], v[16:31]
	ds_read_b128 v[142:145], v186 offset:32320
	v_add_f32_e32 v202, v202, v220
	v_add_f32_e32 v203, v203, v221
	v_cvt_pk_bf16_f32 v213, v220, v221
	v_exp_f32_e32 v42, v42
	v_exp_f32_e32 v43, v43
	v_mfma_f32_32x32x16_bf16 v[0:15], v[162:165], v[210:213], v[0:15]
	ds_read_b128 v[162:165], v186 offset:27744
	v_exp_f32_e32 v44, v44
	v_exp_f32_e32 v45, v45
	v_mfma_f32_32x32x16_bf16 v[16:31], v[132:135], v[210:213], v[16:31]
	ds_read_b128 v[132:135], v186 offset:32352
	v_exp_f32_e32 v46, v46
	v_exp_f32_e32 v47, v47
	s_waitcnt lgkmcnt(7)
	v_mfma_f32_32x32x16_bf16 v[64:79], v[222:225], v[96:99], 0
	ds_read_b128 v[222:225], v186 offset:55296
	v_add_f32_e32 v188, v188, v32
	v_add_f32_e32 v189, v189, v33
	v_cvt_pk_bf16_f32 v32, v32, v33
	v_add_f32_e32 v190, v190, v34
	v_add_f32_e32 v191, v191, v35
	v_cvt_pk_bf16_f32 v33, v34, v35
	v_exp_f32_e32 v48, v48
	v_exp_f32_e32 v49, v49
	s_waitcnt lgkmcnt(7)
	v_mfma_f32_32x32x16_bf16 v[206:221], v[226:229], v[96:99], 0
	ds_read_b128 v[226:229], v186 offset:59904
	v_add_f32_e32 v192, v192, v36
	v_add_f32_e32 v193, v193, v37
	v_cvt_pk_bf16_f32 v34, v36, v37
	v_exp_f32_e32 v50, v50
	v_exp_f32_e32 v51, v51
	s_waitcnt lgkmcnt(7)
	v_mfma_f32_32x32x16_bf16 v[64:79], v[230:233], v[100:103], v[64:79]
	ds_read_b128 v[230:233], v186 offset:55328
	v_add_f32_e32 v194, v194, v38
	v_add_f32_e32 v195, v195, v39
	v_cvt_pk_bf16_f32 v35, v38, v39
	v_exp_f32_e32 v52, v52
	v_exp_f32_e32 v53, v53
	s_waitcnt lgkmcnt(7)
	v_mfma_f32_32x32x16_bf16 v[206:221], v[234:237], v[100:103], v[206:221]
	ds_read_b128 v[234:237], v186 offset:59936
	v_add_f32_e32 v196, v196, v40
	v_add_f32_e32 v197, v197, v41
	v_cvt_pk_bf16_f32 v36, v40, v41
	v_exp_f32_e32 v54, v54
	v_exp_f32_e32 v55, v55
	s_waitcnt lgkmcnt(7)
	v_mfma_f32_32x32x16_bf16 v[64:79], v[138:141], v[104:107], v[64:79]
	ds_read_b128 v[138:141], v186 offset:55360
	v_add_f32_e32 v198, v198, v42
	v_add_f32_e32 v199, v199, v43
	v_cvt_pk_bf16_f32 v37, v42, v43
	v_exp_f32_e32 v56, v56
	v_exp_f32_e32 v57, v57
	s_waitcnt lgkmcnt(7)
	v_mfma_f32_32x32x16_bf16 v[206:221], v[142:145], v[104:107], v[206:221]
	ds_read_b128 v[142:145], v186 offset:59968
	v_add_f32_e32 v200, v200, v44
	v_add_f32_e32 v201, v201, v45
	v_cvt_pk_bf16_f32 v38, v44, v45
	v_exp_f32_e32 v58, v58
	v_exp_f32_e32 v59, v59
	s_waitcnt lgkmcnt(7)
	v_mfma_f32_32x32x16_bf16 v[64:79], v[162:165], v[108:111], v[64:79]
	ds_read_b128 v[162:165], v186 offset:55392
	v_add_f32_e32 v202, v202, v46
	v_add_f32_e32 v203, v203, v47
	v_cvt_pk_bf16_f32 v39, v46, v47
	v_exp_f32_e32 v60, v60
	v_exp_f32_e32 v61, v61
	s_waitcnt lgkmcnt(7)
	v_mfma_f32_32x32x16_bf16 v[206:221], v[132:135], v[108:111], v[206:221]
	ds_read_b128 v[132:135], v186 offset:60000
	v_add_f32_e32 v188, v188, v48
	v_add_f32_e32 v189, v189, v49
	v_cvt_pk_bf16_f32 v48, v48, v49
	v_add_f32_e32 v190, v190, v50
	v_add_f32_e32 v191, v191, v51
	v_cvt_pk_bf16_f32 v49, v50, v51
	v_exp_f32_e32 v62, v62
	v_exp_f32_e32 v63, v63
	s_waitcnt lgkmcnt(7)
	v_mfma_f32_32x32x16_bf16 v[0:15], v[222:225], v[32:35], v[0:15]
	v_add_f32_e32 v192, v192, v52
	v_add_f32_e32 v193, v193, v53
	v_cvt_pk_bf16_f32 v50, v52, v53
	v_exp_f32_e32 v64, v64
	v_exp_f32_e32 v65, v65
	s_waitcnt lgkmcnt(6)
	v_mfma_f32_32x32x16_bf16 v[16:31], v[226:229], v[32:35], v[16:31]
	v_add_f32_e32 v194, v194, v54
	v_add_f32_e32 v195, v195, v55
	v_cvt_pk_bf16_f32 v51, v54, v55
	v_exp_f32_e32 v66, v66
	v_exp_f32_e32 v67, v67
	s_waitcnt lgkmcnt(5)
	v_mfma_f32_32x32x16_bf16 v[0:15], v[230:233], v[36:39], v[0:15]
	v_add_f32_e32 v196, v196, v56
	v_add_f32_e32 v197, v197, v57
	v_cvt_pk_bf16_f32 v52, v56, v57
	v_exp_f32_e32 v68, v68
	v_exp_f32_e32 v69, v69
	s_waitcnt lgkmcnt(4)
	v_mfma_f32_32x32x16_bf16 v[16:31], v[234:237], v[36:39], v[16:31]
	v_add_f32_e32 v198, v198, v58
	v_add_f32_e32 v199, v199, v59
	v_cvt_pk_bf16_f32 v53, v58, v59
	v_exp_f32_e32 v70, v70
	v_exp_f32_e32 v71, v71
	s_waitcnt lgkmcnt(3)
	v_mfma_f32_32x32x16_bf16 v[0:15], v[138:141], v[48:51], v[0:15]
	v_add_f32_e32 v200, v200, v60
	v_add_f32_e32 v201, v201, v61
	v_cvt_pk_bf16_f32 v54, v60, v61
	v_exp_f32_e32 v72, v72
	v_exp_f32_e32 v73, v73
	s_waitcnt lgkmcnt(2)
	v_mfma_f32_32x32x16_bf16 v[16:31], v[142:145], v[48:51], v[16:31]
	v_add_f32_e32 v202, v202, v62
	v_add_f32_e32 v203, v203, v63
	v_cvt_pk_bf16_f32 v55, v62, v63
	v_exp_f32_e32 v74, v74
	v_exp_f32_e32 v75, v75
	s_waitcnt lgkmcnt(1)
	v_mfma_f32_32x32x16_bf16 v[0:15], v[162:165], v[52:55], v[0:15]
	v_exp_f32_e32 v76, v76
	v_exp_f32_e32 v77, v77
	s_waitcnt lgkmcnt(0)
	v_mfma_f32_32x32x16_bf16 v[16:31], v[132:135], v[52:55], v[16:31]
	v_exp_f32_e32 v78, v78
	v_exp_f32_e32 v79, v79
	s_add_i32 s7, s84, 4
	ds_read_b128 v[222:225], v186 offset:64512
	v_add_f32_e32 v188, v188, v64
	v_add_f32_e32 v189, v189, v65
	v_cvt_pk_bf16_f32 v64, v64, v65
	v_add_f32_e32 v190, v190, v66
	v_add_f32_e32 v191, v191, v67
	v_cvt_pk_bf16_f32 v65, v66, v67
	v_exp_f32_e32 v206, v206
	v_exp_f32_e32 v207, v207
	ds_read_b128 v[226:229], v187 offset:32256
	v_add_f32_e32 v192, v192, v68
	v_add_f32_e32 v193, v193, v69
	v_cvt_pk_bf16_f32 v66, v68, v69
	v_exp_f32_e32 v208, v208
	v_exp_f32_e32 v209, v209
	ds_read_b128 v[230:233], v186 offset:64544
	v_add_f32_e32 v194, v194, v70
	v_add_f32_e32 v195, v195, v71
	v_cvt_pk_bf16_f32 v67, v70, v71
	v_exp_f32_e32 v210, v210
	v_exp_f32_e32 v211, v211
	ds_read_b128 v[234:237], v187 offset:32288
	v_add_f32_e32 v196, v196, v72
	v_add_f32_e32 v197, v197, v73
	v_cvt_pk_bf16_f32 v68, v72, v73
	v_exp_f32_e32 v212, v212
	v_exp_f32_e32 v213, v213
	ds_read_b128 v[138:141], v186 offset:64576
	v_add_f32_e32 v198, v198, v74
	v_add_f32_e32 v199, v199, v75
	v_cvt_pk_bf16_f32 v69, v74, v75
	v_exp_f32_e32 v214, v214
	v_exp_f32_e32 v215, v215
	ds_read_b128 v[142:145], v187 offset:32320
	v_add_f32_e32 v200, v200, v76
	v_add_f32_e32 v201, v201, v77
	v_cvt_pk_bf16_f32 v70, v76, v77
	v_exp_f32_e32 v216, v216
	v_exp_f32_e32 v217, v217
	ds_read_b128 v[162:165], v186 offset:64608
	v_add_f32_e32 v202, v202, v78
	v_add_f32_e32 v203, v203, v79
	v_cvt_pk_bf16_f32 v71, v78, v79
	v_exp_f32_e32 v218, v218
	v_exp_f32_e32 v219, v219
	ds_read_b128 v[132:135], v187 offset:32352
	v_add_f32_e32 v188, v188, v206
	v_add_f32_e32 v189, v189, v207
	v_cvt_pk_bf16_f32 v206, v206, v207
	v_add_f32_e32 v190, v190, v208
	v_add_f32_e32 v191, v191, v209
	v_cvt_pk_bf16_f32 v207, v208, v209
	v_exp_f32_e32 v220, v220
	v_exp_f32_e32 v221, v221
	s_waitcnt lgkmcnt(7)
	v_mfma_f32_32x32x16_bf16 v[0:15], v[222:225], v[64:67], v[0:15]
	v_add_f32_e32 v192, v192, v210
	v_add_f32_e32 v193, v193, v211
	v_cvt_pk_bf16_f32 v208, v210, v211
	s_nop 0
	s_nop 0
	s_waitcnt lgkmcnt(6)
	v_mfma_f32_32x32x16_bf16 v[16:31], v[226:229], v[64:67], v[16:31]
	v_add_f32_e32 v194, v194, v212
	v_add_f32_e32 v195, v195, v213
	v_cvt_pk_bf16_f32 v209, v212, v213
	s_nop 0
	s_nop 0
	s_waitcnt lgkmcnt(5)
	v_mfma_f32_32x32x16_bf16 v[0:15], v[230:233], v[68:71], v[0:15]
	v_add_f32_e32 v196, v196, v214
	v_add_f32_e32 v197, v197, v215
	v_cvt_pk_bf16_f32 v210, v214, v215
	s_nop 0
	s_nop 0
	s_waitcnt lgkmcnt(4)
	v_mfma_f32_32x32x16_bf16 v[16:31], v[234:237], v[68:71], v[16:31]
	s_waitcnt lgkmcnt(0)
	s_barrier
	v_add_f32_e32 v198, v198, v216
	v_add_f32_e32 v199, v199, v217
	v_cvt_pk_bf16_f32 v211, v216, v217
	s_nop 0
	s_nop 0
	v_mfma_f32_32x32x16_bf16 v[0:15], v[138:141], v[206:209], v[0:15]
	v_add_f32_e32 v200, v200, v218
	v_add_f32_e32 v201, v201, v219
	v_cvt_pk_bf16_f32 v212, v218, v219
	s_nop 0
	s_nop 0
	v_mfma_f32_32x32x16_bf16 v[16:31], v[142:145], v[206:209], v[16:31]
	v_add_f32_e32 v202, v202, v220
	v_add_f32_e32 v203, v203, v221
	v_cvt_pk_bf16_f32 v213, v220, v221
	s_nop 0
	s_nop 0
	v_mfma_f32_32x32x16_bf16 v[0:15], v[162:165], v[210:213], v[0:15]
	v_mfma_f32_32x32x16_bf16 v[16:31], v[132:135], v[210:213], v[16:31]

; __global__ void __launch_bounds__(NWAVES * 64, 2) mega_fwd(Args a_unused) {
	.amdhsa_kernel _Z8mega_fwd4Args
		.amdhsa_group_segment_fixed_size 0
		.amdhsa_private_segment_fixed_size 0
		.amdhsa_kernarg_size 400
		.amdhsa_user_sgpr_count 2
		.amdhsa_user_sgpr_dispatch_ptr 0
		.amdhsa_user_sgpr_queue_ptr 0
		.amdhsa_user_sgpr_kernarg_segment_ptr 1
		.amdhsa_user_sgpr_dispatch_id 0
		.amdhsa_user_sgpr_kernarg_preload_length 0
		.amdhsa_user_sgpr_kernarg_preload_offset 0
		.amdhsa_user_sgpr_private_segment_size 0
		.amdhsa_uses_dynamic_stack 0
		.amdhsa_enable_private_segment 0
		.amdhsa_system_sgpr_workgroup_id_x 1
		.amdhsa_system_sgpr_workgroup_id_y 0
		.amdhsa_system_sgpr_workgroup_id_z 0
		.amdhsa_system_sgpr_workgroup_info 0
		.amdhsa_system_vgpr_workitem_id 2
		.amdhsa_next_free_vgpr 255
		.amdhsa_next_free_sgpr 102
		.amdhsa_accum_offset 256
		.amdhsa_reserve_vcc 1
		.amdhsa_float_round_mode_32 0
		.amdhsa_float_round_mode_16_64 0
		.amdhsa_float_denorm_mode_32 3
		.amdhsa_float_denorm_mode_16_64 3
		.amdhsa_dx10_clamp 1
		.amdhsa_ieee_mode 1
		.amdhsa_fp16_overflow 0
		.amdhsa_tg_split 0
		.amdhsa_exception_fp_ieee_invalid_op 0
		.amdhsa_exception_fp_denorm_src 0
		.amdhsa_exception_fp_ieee_div_zero 0
		.amdhsa_exception_fp_ieee_overflow 0
		.amdhsa_exception_fp_ieee_underflow 0
		.amdhsa_exception_fp_ieee_inexact 0
		.amdhsa_exception_int_div_zero 0
	.end_amdhsa_kernel

; __global__ void __launch_bounds__(NWAVES * 64, 2) mega_fwd(Args a_unused) {
amdhsa.kernels:
  - .agpr_count:     0
    .args:
      - .offset:         0
        .size:           144
        .value_kind:     by_value
      - .offset:         144
        .size:           4
        .value_kind:     hidden_block_count_x
      - .offset:         148
        .size:           4
        .value_kind:     hidden_block_count_y
      - .offset:         152
        .size:           4
        .value_kind:     hidden_block_count_z
      - .offset:         156
        .size:           2
        .value_kind:     hidden_group_size_x
      - .offset:         158
        .size:           2
        .value_kind:     hidden_group_size_y
      - .offset:         160
        .size:           2
        .value_kind:     hidden_group_size_z
      - .offset:         162
        .size:           2
        .value_kind:     hidden_remainder_x
      - .offset:         164
        .size:           2
        .value_kind:     hidden_remainder_y
      - .offset:         166
        .size:           2
        .value_kind:     hidden_remainder_z
      - .offset:         184
        .size:           8
        .value_kind:     hidden_global_offset_x
      - .offset:         192
        .size:           8
        .value_kind:     hidden_global_offset_y
      - .offset:         200
        .size:           8
        .value_kind:     hidden_global_offset_z
      - .offset:         208
        .size:           2
        .value_kind:     hidden_grid_dims
      - .offset:         232
        .size:           8
        .value_kind:     hidden_multigrid_sync_arg
      - .offset:         264
        .size:           4
        .value_kind:     hidden_dynamic_lds_size
    .group_segment_fixed_size: 0
    .kernarg_segment_align: 8
    .kernarg_segment_size: 400
    .language:       OpenCL C
    .language_version:
      - 2
      - 0
    .max_flat_workgroup_size: 512
    .name:           _Z8mega_fwd4Args
    .private_segment_fixed_size: 0
    .sgpr_count:     108
    .sgpr_spill_count: 4
    .symbol:         _Z8mega_fwd4Args.kd
    .uniform_work_group_size: 1
    .uses_dynamic_stack: false
    .vgpr_count:     255
    .vgpr_spill_count: 0
    .wavefront_size: 64
